# removed the redundant workgroup barrier before the tile-0 LDS-DMA in the MLA and diff unit prologues (K/V buffers are already free after the previous loop's last barrier; exchange region is disjoint)
# baseline (speedup 1.0000x reference)
.LBB0_132:
	s_and_b32 s5, s64, 7
	s_lshl_b32 s0, s5, 8
	s_or_b32 s22, s14, s0
	s_mov_b32 s23, s15
	s_lshl_b64 s[0:1], s[22:23], 10
	s_add_u32 s0, s55, s0
	s_addc_u32 s1, s56, s1
	s_lshl_b32 s4, s64, 4
	s_and_b32 s65, s4, 0x180
	s_lshl_b32 s4, s65, 1
	s_add_u32 s30, s0, s4
	s_addc_u32 s31, s1, 0
	s_lshl_b64 s[0:1], s[2:3], 21
	s_add_u32 s3, s57, s0
	s_addc_u32 s6, s58, s1
	s_add_u32 s24, s3, s4
	s_addc_u32 s25, s6, 0
	v_mov_b32_e32 v121, v218
	s_add_u32 s0, s90, s0
	v_mov_b32_e32 v4, v218
	s_addc_u32 s1, s91, s1
	s_add_u32 s3, s0, s4
	v_ashrrev_i32_e32 v0, 6, v4
	v_and_b32_e32 v6, 31, v4
	v_readfirstlane_b32 s0, v0
	v_lshl_or_b32 v0, v0, 5, v6
	v_ashrrev_i32_e32 v1, 31, v0
	v_lshlrev_b64 v[0:1], 10, v[0:1]
	v_lshrrev_b32_e32 v7, 1, v4
	v_and_b32_e32 v5, 63, v4
	v_lshl_add_u64 v[0:1], s[30:31], 0, v[0:1]
	v_and_b32_e32 v184, 16, v7
	s_addc_u32 s66, s1, 0
	v_lshl_add_u64 v[0:1], v[0:1], 0, v[184:185]
	s_lshl_b32 s1, s0, 10
	v_lshlrev_b32_e32 v8, 4, v5
	global_load_dwordx4 v[96:99], v[0:1], off
	global_load_dwordx4 v[100:103], v[0:1], off offset:32
	global_load_dwordx4 v[104:107], v[0:1], off offset:64
	global_load_dwordx4 v[108:111], v[0:1], off offset:96
	v_or_b32_e32 v0, s1, v8
	v_ashrrev_i32_e32 v1, 31, v0
	v_lshrrev_b32_e32 v1, 25, v1
	v_add_u32_e32 v1, v0, v1
	v_lshlrev_b32_e32 v9, 3, v5
	s_lshl_b32 s0, s0, 6
	v_ashrrev_i32_e32 v2, 7, v1
	v_and_b32_e32 v1, 0xffffff80, v1
	v_and_b32_e32 v3, 32, v4
	s_and_b32 s0, s0, 64
	v_and_b32_e32 v10, 24, v9
	v_sub_u32_e32 v0, v0, v1
	v_or3_b32 v3, v10, v3, s0
	s_ashr_i32 s0, s1, 8
	v_ashrrev_i32_e32 v0, 4, v0
	v_lshrrev_b32_e32 v1, 1, v2
	s_and_b32 s6, s0, 0x7ffff0
	s_lshr_b32 s0, s0, 1
	v_bitop3_b32 v0, v1, v0, 7 bitop3:0x6c
	v_bfe_u32 v1, v4, 2, 2
	s_and_b32 s0, s0, 4
	v_and_or_b32 v1, v7, 8, v1
	s_or_b32 s0, s6, s0
	v_or_b32_e32 v10, s0, v1
	s_add_i32 s0, s1, 0x2000
	s_ashr_i32 s0, s0, 8
	s_and_b32 s6, s0, 0x7ffff0
	s_lshr_b32 s0, s0, 1
	s_and_b32 s0, s0, 4
	s_or_b32 s0, s6, s0
	s_add_i32 s4, 0, 0x14000
	v_or_b32_e32 v1, s0, v1
	s_lshl_b32 s0, s5, 17
	s_lshl_b32 s6, s5, 18
	v_lshl_or_b32 v114, v1, 9, v3
	v_lshlrev_b32_e32 v1, 9, v2
	s_add_u32 s68, s24, s6
	v_lshl_add_u32 v0, v0, 3, v1
	s_addc_u32 s69, s25, 0
	s_add_i32 s5, s1, 0
	v_ashrrev_i32_e32 v1, 31, v0
	s_add_i32 m0, s5, 0x8000
	v_lshl_or_b32 v112, v10, 9, v3
	v_lshlrev_b64 v[0:1], 1, v[0:1]
	s_add_u32 s34, s3, s6
	v_lshl_add_u64 v[2:3], s[68:69], 0, v[0:1]
	s_addc_u32 s35, s66, 0
	v_ashrrev_i32_e32 v113, 31, v112
	s_waitcnt lgkmcnt(0)
	global_load_lds_dwordx4 v[2:3], off
	v_lshl_add_u64 v[2:3], v[112:113], 1, s[34:35]
	s_mov_b32 m0, s5
	v_ashrrev_i32_e32 v115, 31, v114
	global_load_lds_dwordx4 v[2:3], off
	v_lshl_add_u64 v[2:3], v[114:115], 1, s[34:35]
	s_add_i32 m0, s5, 0x2000
	s_cmp_lg_u32 0, -1
	global_load_lds_dwordx4 v[2:3], off
	v_and_b32_e32 v2, 0x3fffffc0, v4
	v_lshl_add_u32 v119, v2, 2, s4
	v_lshlrev_b32_e32 v2, 1, v4
	s_cselect_b32 s1, 0, 0
	v_and_b32_e32 v2, 32, v2
	v_lshlrev_b32_e32 v4, 3, v4
	s_add_i32 s6, s1, 0x8000
	s_movk_i32 s54, 0x118
	v_and_b32_e32 v3, 0xc0, v8
	v_and_b32_e32 v4, 0x70, v4
	v_lshl_add_u32 v120, v6, 7, s6
	s_movk_i32 s6, 0x60
	v_lshl_add_u64 v[116:117], s[24:25], 0, v[0:1]
	v_mov_b32_e32 v194, v0
	v_lshlrev_b32_e32 v195, 1, v112
	v_lshlrev_b32_e32 v196, 1, v114
	v_and_or_b32 v0, v9, s54, v2
	v_mov_b32_e32 v14, v185
	v_mov_b32_e32 v15, v185
	v_bitop3_b32 v123, v7, v4, 16 bitop3:0x6c
	v_bitop3_b32 v124, v184, v4, 32 bitop3:0x36
	v_bitop3_b32 v125, v184, v4, 64 bitop3:0x36
	v_bitop3_b32 v126, v184, v4, s6 bitop3:0x36
	v_cmp_gt_u32_e64 s[6:7], 32, v5
	v_lshl_add_u32 v122, v6, 2, v119
	v_add3_u32 v127, v3, s1, v0
	s_or_b32 s67, s0, 0x8000
	v_mov_b32_e32 v0, v185
	v_mov_b32_e32 v1, v185
	v_mov_b32_e32 v2, v185
	v_mov_b32_e32 v3, v185
	v_mov_b32_e32 v4, v185
	v_mov_b32_e32 v5, v185
	v_mov_b32_e32 v6, v185
	v_mov_b32_e32 v7, v185
	v_mov_b32_e32 v8, v185
	v_mov_b32_e32 v9, v185
	v_mov_b32_e32 v10, v185
	v_mov_b32_e32 v11, v185
	v_mov_b32_e32 v12, v185
	v_mov_b32_e32 v13, v185
	v_mov_b64_e32 v[30:31], v[14:15]
	v_mov_b64_e32 v[46:47], v[14:15]
	v_mov_b64_e32 v[62:63], v[14:15]
	s_mov_b32 s53, 0
	v_mov_b32_e32 v128, 0
	v_mov_b32_e32 v160, 0x80000000
	v_mov_b32_e32 v161, 0x80000000
	v_mov_b32_e32 v162, 0x80000000
	v_mov_b32_e32 v163, 0x80000000
	v_mov_b32_e32 v164, 0x80000000
	v_mov_b32_e32 v165, 0x80000000
	v_mov_b32_e32 v166, 0x80000000
	v_mov_b32_e32 v167, 0x80000000
	v_mov_b32_e32 v168, 0x80000000
	v_mov_b32_e32 v169, 0x80000000
	v_mov_b32_e32 v170, 0x80000000
	v_mov_b32_e32 v171, 0x80000000
	v_mov_b32_e32 v172, 0x80000000
	v_mov_b32_e32 v173, 0x80000000
	v_mov_b32_e32 v174, 0x80000000
	v_mov_b32_e32 v175, 0x80000000
	s_mov_b32 s54, s67
	v_mov_b64_e32 v[28:29], v[12:13]
	v_mov_b64_e32 v[26:27], v[10:11]
	v_mov_b64_e32 v[24:25], v[8:9]
	v_mov_b64_e32 v[22:23], v[6:7]
	v_mov_b64_e32 v[20:21], v[4:5]
	v_mov_b64_e32 v[18:19], v[2:3]
	v_mov_b64_e32 v[16:17], v[0:1]
	v_mov_b64_e32 v[44:45], v[12:13]
	v_mov_b64_e32 v[42:43], v[10:11]
	v_mov_b64_e32 v[40:41], v[8:9]
	v_mov_b64_e32 v[38:39], v[6:7]
	v_mov_b64_e32 v[36:37], v[4:5]
	v_mov_b64_e32 v[34:35], v[2:3]
	v_mov_b64_e32 v[32:33], v[0:1]
	v_mov_b64_e32 v[60:61], v[12:13]
	v_mov_b64_e32 v[58:59], v[10:11]
	v_mov_b64_e32 v[56:57], v[8:9]
	v_mov_b64_e32 v[54:55], v[6:7]
	v_mov_b64_e32 v[52:53], v[4:5]
	v_mov_b64_e32 v[50:51], v[2:3]
	v_mov_b64_e32 v[48:49], v[0:1]
	v_mov_b32_e32 v129, 0
	s_waitcnt vmcnt(0) lgkmcnt(0)
	s_barrier
	s_and_b32 s80, s53, 1
	v_add_u32_e32 v118, v120, v123
	ds_read_b128 v[130:133], v118 offset:0
	ds_read_b128 v[134:137], v118 offset:0x1000
	v_add_u32_e32 v210, v120, v124
	ds_read_b128 v[202:205], v210 offset:0
	ds_read_b128 v[206:209], v210 offset:0x1000
	s_cmp_eq_u32 s53, 31
	s_movk_i32 s0, 0x2000
	s_cbranch_scc1 .LBB0_134

.LBB0_169:
	s_and_b32 s0, s64, 31
	s_lshl_b32 s0, s0, 6
	s_or_b32 s14, s14, s0
	s_mul_i32 s0, s15, 0x600
	s_mul_hi_u32 s1, s14, 0x600
	s_add_i32 s1, s1, s0
	s_mul_i32 s0, s14, 0x600
	s_add_u32 s0, s38, s0
	s_addc_u32 s1, s39, s1
	s_mul_hi_i32 s3, s2, 0xc0000
	s_mul_i32 s2, s2, 0xc0000
	v_mov_b32_e32 v158, v218
	s_add_u32 s4, s28, s2
	v_mov_b32_e32 v4, v218
	s_addc_u32 s5, s29, s3
	s_add_i32 s3, 0, 0x14000
	v_and_b32_e32 v0, 0x3fffffc0, v4
	v_lshl_add_u32 v159, v0, 2, s3
	v_ashrrev_i32_e32 v0, 6, v4
	v_and_b32_e32 v6, 31, v4
	v_readfirstlane_b32 s3, v0
	v_lshlrev_b32_e32 v0, 5, v0
	v_and_or_b32 v0, v0, 32, v6
	v_mul_u32_u24_e32 v0, 0x300, v0
	v_ashrrev_i32_e32 v2, 7, v4
	v_lshlrev_b32_e32 v184, 1, v0
	v_mul_lo_u32 v2, v2, s60
	v_lshl_add_u64 v[0:1], s[0:1], 0, v[184:185]
	v_ashrrev_i32_e32 v3, 31, v2
	v_lshl_add_u64 v[0:1], v[2:3], 1, v[0:1]
	v_lshrrev_b32_e32 v2, 1, v4
	v_and_b32_e32 v5, 63, v4
	v_and_b32_e32 v184, 16, v2
	v_lshl_add_u64 v[0:1], v[0:1], 0, v[184:185]
	s_lshl_b32 s6, s3, 10
	v_lshlrev_b32_e32 v3, 4, v5
	global_load_dwordx4 v[96:99], v[0:1], off
	global_load_dwordx4 v[100:103], v[0:1], off offset:32
	global_load_dwordx4 v[104:107], v[0:1], off offset:64
	global_load_dwordx4 v[108:111], v[0:1], off offset:96
	global_load_dwordx4 v[112:115], v[0:1], off offset:128
	global_load_dwordx4 v[116:119], v[0:1], off offset:160
	global_load_dwordx4 v[120:123], v[0:1], off offset:192
	global_load_dwordx4 v[124:127], v[0:1], off offset:224
	global_load_dwordx4 v[128:131], v[0:1], off offset:256
	global_load_dwordx4 v[132:135], v[0:1], off offset:288
	global_load_dwordx4 v[136:139], v[0:1], off offset:320
	global_load_dwordx4 v[140:143], v[0:1], off offset:352
	v_or_b32_e32 v0, s6, v3
	s_mov_b32 s0, 0x2aaaaaab
	v_mul_hi_i32 v1, v0, s0
	v_lshrrev_b32_e32 v7, 31, v1
	v_ashrrev_i32_e32 v1, 6, v1
	v_add_u32_e32 v1, v1, v7
	v_mul_i32_i24_e32 v7, 0x180, v1
	v_sub_u32_e32 v7, v0, v7
	v_ashrrev_i32_e32 v7, 4, v7
	v_lshrrev_b32_e32 v8, 1, v1
	v_bitop3_b32 v7, v8, v7, 7 bitop3:0x6c
	v_mul_i32_i24_e32 v1, 0xc0, v1
	v_lshl_add_u32 v146, v7, 3, v1
	v_add_u32_e32 v1, 0x2000, v0
	v_mul_hi_i32 v7, v1, s0
	v_lshrrev_b32_e32 v8, 31, v7
	v_ashrrev_i32_e32 v7, 6, v7
	v_add_u32_e32 v7, v7, v8
	v_mul_i32_i24_e32 v8, 0x180, v7
	v_sub_u32_e32 v1, v1, v8
	v_ashrrev_i32_e32 v1, 4, v1
	v_lshrrev_b32_e32 v8, 1, v7
	v_bitop3_b32 v1, v8, v1, 7 bitop3:0x6c
	v_mul_i32_i24_e32 v7, 0xc0, v7
	v_add_u32_e32 v0, 0x4000, v0
	v_lshl_add_u32 v148, v1, 3, v7
	v_mul_hi_i32 v1, v0, s0
	v_lshrrev_b32_e32 v7, 31, v1
	v_ashrrev_i32_e32 v1, 6, v1
	v_add_u32_e32 v1, v1, v7
	v_mul_i32_i24_e32 v7, 0x180, v1
	v_sub_u32_e32 v0, v0, v7
	v_ashrrev_i32_e32 v0, 4, v0
	v_lshrrev_b32_e32 v7, 1, v1
	v_bitop3_b32 v0, v7, v0, 7 bitop3:0x6c
	v_mul_i32_i24_e32 v1, 0xc0, v1
	v_lshlrev_b32_e32 v7, 3, v5
	s_lshl_b32 s0, s3, 6
	v_lshl_add_u32 v150, v0, 3, v1
	v_and_b32_e32 v1, 32, v4
	s_and_b32 s0, s0, 64
	v_and_b32_e32 v8, 24, v7
	v_or3_b32 v1, v8, v1, s0
	s_ashr_i32 s0, s6, 8
	s_and_b32 s1, s0, 0xfffff0
	s_lshr_b32 s0, s0, 1
	v_bfe_u32 v0, v4, 2, 2
	s_and_b32 s0, s0, 4
	v_and_or_b32 v0, v2, 8, v0
	s_or_b32 s0, s1, s0
	v_or_b32_e32 v8, s0, v0
	s_add_i32 s0, s6, 0x2000
	s_ashr_i32 s0, s0, 8
	s_lshl_b32 s2, s64, 2
	s_and_b32 s1, s0, 0xfffff0
	s_lshr_b32 s0, s0, 1
	s_and_b32 s2, s2, 28
	s_and_b32 s0, s0, 4
	s_or_b32 s0, s1, s0
	s_mulk_i32 s2, 0x6000
	v_or_b32_e32 v0, s0, v0
	s_add_u32 s0, s4, s2
	s_addc_u32 s1, s5, 0
	s_add_i32 s30, s6, 0
	v_ashrrev_i32_e32 v147, 31, v146
	v_mad_i32_i24 v152, v8, s60, v1
	v_mad_i32_i24 v154, v0, s60, v1
	s_add_i32 m0, s30, 0x8000
	v_lshl_add_u64 v[0:1], v[146:147], 1, s[0:1]
	v_ashrrev_i32_e32 v149, 31, v148
	s_waitcnt lgkmcnt(0)
	global_load_lds_dwordx4 v[0:1], off
	v_lshl_add_u64 v[0:1], v[148:149], 1, s[0:1]
	s_add_i32 m0, s30, 0xa000
	v_ashrrev_i32_e32 v151, 31, v150
	global_load_lds_dwordx4 v[0:1], off
	v_lshl_add_u64 v[0:1], v[150:151], 1, s[0:1]
	s_add_i32 m0, s30, 0xc000
	v_ashrrev_i32_e32 v153, 31, v152
	global_load_lds_dwordx4 v[0:1], off
	v_lshl_add_u64 v[0:1], v[152:153], 1, s[0:1]
	s_mov_b32 m0, s30
	v_ashrrev_i32_e32 v155, 31, v154
	global_load_lds_dwordx4 v[0:1], off
	v_lshl_add_u64 v[0:1], v[154:155], 1, s[0:1]
	s_add_i32 m0, s30, 0x2000
	s_cmp_lg_u32 0, -1
	global_load_lds_dwordx4 v[0:1], off
	s_cselect_b32 s0, 0, 0
	s_add_i32 s1, s0, 0x8000
	v_lshlrev_b32_e32 v8, 1, v4
	v_lshlrev_b32_e32 v1, 3, v4
	v_mov_b32_e32 v4, s1
	s_movk_i32 s1, 0x180
	v_and_b32_e32 v1, 0x70, v1
	v_mad_u32_u24 v161, v6, s1, v4
	s_movk_i32 s1, 0x60
	v_and_b32_e32 v0, 32, v8
	v_bitop3_b32 v165, v184, v1, s1 bitop3:0x36
	s_movk_i32 s1, 0x118
	v_and_b32_e32 v3, 0xc0, v3
	v_and_or_b32 v0, v7, s1, v0
	v_add3_u32 v166, v3, s0, v0
	s_and_b32 s0, s64, 7
	v_mov_b32_e32 v14, v185
	v_mov_b32_e32 v15, v185
	v_bitop3_b32 v162, v2, v1, 16 bitop3:0x6c
	v_bitop3_b32 v163, v184, v1, 32 bitop3:0x36
	v_bitop3_b32 v164, v184, v1, 64 bitop3:0x36
	v_cmp_gt_u32_e64 s[6:7], 32, v5
	v_lshl_add_u32 v160, v6, 2, v159
	s_lshl_b32 s0, s0, 8
	v_mov_b32_e32 v0, v185
	v_mov_b32_e32 v1, v185
	v_mov_b32_e32 v2, v185
	v_mov_b32_e32 v3, v185
	v_mov_b32_e32 v4, v185
	v_mov_b32_e32 v5, v185
	v_mov_b32_e32 v6, v185
	v_mov_b32_e32 v7, v185
	v_mov_b32_e32 v8, v185
	v_mov_b32_e32 v9, v185
	v_mov_b32_e32 v10, v185
	v_mov_b32_e32 v11, v185
	v_mov_b32_e32 v12, v185
	v_mov_b32_e32 v13, v185
	v_mov_b64_e32 v[30:31], v[14:15]
	v_mov_b64_e32 v[46:47], v[14:15]
	v_mov_b64_e32 v[62:63], v[14:15]
	s_mov_b32 s31, 0
	s_or_b32 s34, s0, 64
	v_lshlrev_b32_e32 v197, 1, v146
	v_lshlrev_b32_e32 v198, 1, v148
	v_lshlrev_b32_e32 v199, 1, v150
	v_lshlrev_b32_e32 v200, 1, v152
	v_lshlrev_b32_e32 v201, 1, v154
	v_mov_b32_e32 v167, 0
	v_mov_b64_e32 v[28:29], v[12:13]
	v_mov_b64_e32 v[26:27], v[10:11]
	v_mov_b64_e32 v[24:25], v[8:9]
	v_mov_b64_e32 v[22:23], v[6:7]
	v_mov_b64_e32 v[20:21], v[4:5]
	v_mov_b64_e32 v[18:19], v[2:3]
	v_mov_b64_e32 v[16:17], v[0:1]
	v_mov_b64_e32 v[44:45], v[12:13]
	v_mov_b64_e32 v[42:43], v[10:11]
	v_mov_b64_e32 v[40:41], v[8:9]
	v_mov_b64_e32 v[38:39], v[6:7]
	v_mov_b64_e32 v[36:37], v[4:5]
	v_mov_b64_e32 v[34:35], v[2:3]
	v_mov_b64_e32 v[32:33], v[0:1]
	v_mov_b64_e32 v[60:61], v[12:13]
	v_mov_b64_e32 v[58:59], v[10:11]
	v_mov_b64_e32 v[56:57], v[8:9]
	v_mov_b64_e32 v[54:55], v[6:7]
	v_mov_b64_e32 v[52:53], v[4:5]
	v_mov_b64_e32 v[50:51], v[2:3]
	v_mov_b64_e32 v[48:49], v[0:1]
	v_mov_b32_e32 v168, 0
	s_waitcnt vmcnt(0) lgkmcnt(0)
	s_barrier
	s_and_b32 s35, s31, 1
	s_cmp_eq_u32 s31, 31
	s_cbranch_scc1 .LBB0_171
